# grid barrier: drop the per-XCD generation increment (nobody polls it since non-leaders read the cross-XCD word)
# speedup vs baseline: 1.0061x; 1.0061x over previous
; __device__ __forceinline__ unsigned xb_ld(unsigned* p)              { return __hip_atomic_load(p, __ATOMIC_RELAXED, __HIP_MEMORY_SCOPE_AGENT); }
; __device__ __forceinline__ unsigned xb_add(unsigned* p, unsigned v) { return __hip_atomic_fetch_add(p, v, __ATOMIC_RELAXED, __HIP_MEMORY_SCOPE_AGENT); }
; #define XB_SPIN(cond, bar) do { unsigned _sp = 0; while (cond) { __builtin_amdgcn_s_sleep(1); \
;     if ((++_sp & 255u) == 0u) { if (xb_ld(&(bar)[XB_TMO])) break; if (_sp > XB_SPIN_CAP) { atomicAdd(&(bar)[XB_TMO], 1u); break; } } } } while (0)
; __device__ __forceinline__ void xcd_barrier(const XcdBarrier& b) {
;     ...
;         const unsigned old = xb_add(&bar[XB_XSUB(b.x)], 1u);
;         const unsigned gen = old / nloc;
;         if (old + 1u == (gen + 1u) * nloc) {
;             __builtin_amdgcn_fence(__ATOMIC_RELEASE, "agent");
;             asm volatile("s_waitcnt vmcnt(0)" ::: "memory");
;             const unsigned og = xb_add(&bar[XB_TOP], 1u);
;             const unsigned tg = og / nx;
;             if (og + 1u == (tg + 1u) * nx) xb_add(&bar[XB_TOPGEN], 1u);
;             else XB_SPIN(xb_ld(&bar[XB_TOPGEN]) == tg, bar);
;             __builtin_amdgcn_fence(__ATOMIC_ACQUIRE, "agent");
;             xb_add(&bar[XB_XGEN(b.x)], 1u);
;             asm volatile("s_waitcnt vmcnt(0)" ::: "memory");
.LBB0_77:
	s_or_b64 exec, exec, s[6:7]
	s_mov_b64 s[6:7], exec
	v_mbcnt_lo_u32_b32 v0, s6, 0
	v_mbcnt_hi_u32_b32 v0, s7, v0
	v_cmp_eq_u32_e32 vcc, 0, v0
	s_waitcnt vmcnt(0)
	s_and_saveexec_b64 s[10:11], vcc
	s_cbranch_execz .LBB0_79
	s_bcnt1_i32_b64 s0, s[6:7]
	v_mov_b32_e32 v0, 0x2000
	v_mov_b32_e32 v1, s0
	s_nop 0

; __device__ __forceinline__ unsigned xb_ld(unsigned* p)              { return __hip_atomic_load(p, __ATOMIC_RELAXED, __HIP_MEMORY_SCOPE_AGENT); }
; __device__ __forceinline__ unsigned xb_add(unsigned* p, unsigned v) { return __hip_atomic_fetch_add(p, v, __ATOMIC_RELAXED, __HIP_MEMORY_SCOPE_AGENT); }
; #define XB_SPIN(cond, bar) do { unsigned _sp = 0; while (cond) { __builtin_amdgcn_s_sleep(1); \
;     if ((++_sp & 255u) == 0u) { if (xb_ld(&(bar)[XB_TMO])) break; if (_sp > XB_SPIN_CAP) { atomicAdd(&(bar)[XB_TMO], 1u); break; } } } } while (0)
; __device__ __forceinline__ void xcd_barrier(const XcdBarrier& b) {
;     ...
;             const unsigned og = xb_add(&bar[XB_TOP], 1u);
;             const unsigned tg = og / nx;
;             if (og + 1u == (tg + 1u) * nx) xb_add(&bar[XB_TOPGEN], 1u);
;             else XB_SPIN(xb_ld(&bar[XB_TOPGEN]) == tg, bar);
;             __builtin_amdgcn_fence(__ATOMIC_ACQUIRE, "agent");
;             xb_add(&bar[XB_XGEN(b.x)], 1u);
;             asm volatile("s_waitcnt vmcnt(0)" ::: "memory");
.LBB0_265:
	s_or_b64 exec, exec, s[8:9]
	s_mov_b64 s[8:9], exec
	v_mbcnt_lo_u32_b32 v0, s8, 0
	v_mbcnt_hi_u32_b32 v0, s9, v0
	v_cmp_eq_u32_e32 vcc, 0, v0
	s_waitcnt vmcnt(0)
	s_and_saveexec_b64 s[12:13], vcc
	s_cbranch_execz .LBB0_267
	s_bcnt1_i32_b64 s0, s[8:9]
	v_mov_b32_e32 v0, s0
	v_mov_b32_e32 v2, 0x2000
	s_nop 0

; __device__ __forceinline__ unsigned xb_ld(unsigned* p)              { return __hip_atomic_load(p, __ATOMIC_RELAXED, __HIP_MEMORY_SCOPE_AGENT); }
; __device__ __forceinline__ unsigned xb_add(unsigned* p, unsigned v) { return __hip_atomic_fetch_add(p, v, __ATOMIC_RELAXED, __HIP_MEMORY_SCOPE_AGENT); }
; #define XB_SPIN(cond, bar) do { unsigned _sp = 0; while (cond) { __builtin_amdgcn_s_sleep(1); \
;     if ((++_sp & 255u) == 0u) { if (xb_ld(&(bar)[XB_TMO])) break; if (_sp > XB_SPIN_CAP) { atomicAdd(&(bar)[XB_TMO], 1u); break; } } } } while (0)
; __device__ __forceinline__ void xcd_barrier(const XcdBarrier& b) {
;     ...
;             const unsigned og = xb_add(&bar[XB_TOP], 1u);
;             const unsigned tg = og / nx;
;             if (og + 1u == (tg + 1u) * nx) xb_add(&bar[XB_TOPGEN], 1u);
;             else XB_SPIN(xb_ld(&bar[XB_TOPGEN]) == tg, bar);
;             __builtin_amdgcn_fence(__ATOMIC_ACQUIRE, "agent");
;             xb_add(&bar[XB_XGEN(b.x)], 1u);
;             asm volatile("s_waitcnt vmcnt(0)" ::: "memory");
.LBB0_358:
	s_or_b64 exec, exec, s[8:9]
	s_mov_b64 s[8:9], exec
	v_mbcnt_lo_u32_b32 v0, s8, 0
	v_mbcnt_hi_u32_b32 v0, s9, v0
	v_cmp_eq_u32_e32 vcc, 0, v0
	s_waitcnt vmcnt(0)
	s_and_saveexec_b64 s[14:15], vcc
	s_cbranch_execz .LBB0_360
	s_bcnt1_i32_b64 s0, s[8:9]
	v_mov_b32_e32 v0, s0
	v_mov_b32_e32 v2, 0x2000
	s_nop 0

; __device__ __forceinline__ unsigned xb_ld(unsigned* p)              { return __hip_atomic_load(p, __ATOMIC_RELAXED, __HIP_MEMORY_SCOPE_AGENT); }
; __device__ __forceinline__ unsigned xb_add(unsigned* p, unsigned v) { return __hip_atomic_fetch_add(p, v, __ATOMIC_RELAXED, __HIP_MEMORY_SCOPE_AGENT); }
; #define XB_SPIN(cond, bar) do { unsigned _sp = 0; while (cond) { __builtin_amdgcn_s_sleep(1); \
;     if ((++_sp & 255u) == 0u) { if (xb_ld(&(bar)[XB_TMO])) break; if (_sp > XB_SPIN_CAP) { atomicAdd(&(bar)[XB_TMO], 1u); break; } } } } while (0)
; __device__ __forceinline__ void xcd_barrier(const XcdBarrier& b) {
;     ...
;             const unsigned og = xb_add(&bar[XB_TOP], 1u);
;             const unsigned tg = og / nx;
;             if (og + 1u == (tg + 1u) * nx) xb_add(&bar[XB_TOPGEN], 1u);
;             else XB_SPIN(xb_ld(&bar[XB_TOPGEN]) == tg, bar);
;             __builtin_amdgcn_fence(__ATOMIC_ACQUIRE, "agent");
;             xb_add(&bar[XB_XGEN(b.x)], 1u);
;             asm volatile("s_waitcnt vmcnt(0)" ::: "memory");
.LBB0_475:
	s_or_b64 exec, exec, s[6:7]
	s_mov_b64 s[6:7], exec
	v_mbcnt_lo_u32_b32 v0, s6, 0
	v_mbcnt_hi_u32_b32 v0, s7, v0
	v_cmp_eq_u32_e32 vcc, 0, v0
	s_waitcnt vmcnt(0)
	s_and_saveexec_b64 s[12:13], vcc
	s_cbranch_execz .LBB0_477
	s_bcnt1_i32_b64 s0, s[6:7]
	v_mov_b32_e32 v0, s0
	v_mov_b32_e32 v2, 0x2000
	s_nop 0

; __device__ __forceinline__ unsigned xb_ld(unsigned* p)              { return __hip_atomic_load(p, __ATOMIC_RELAXED, __HIP_MEMORY_SCOPE_AGENT); }
; __device__ __forceinline__ unsigned xb_add(unsigned* p, unsigned v) { return __hip_atomic_fetch_add(p, v, __ATOMIC_RELAXED, __HIP_MEMORY_SCOPE_AGENT); }
; #define XB_SPIN(cond, bar) do { unsigned _sp = 0; while (cond) { __builtin_amdgcn_s_sleep(1); \
;     if ((++_sp & 255u) == 0u) { if (xb_ld(&(bar)[XB_TMO])) break; if (_sp > XB_SPIN_CAP) { atomicAdd(&(bar)[XB_TMO], 1u); break; } } } } while (0)
; __device__ __forceinline__ void xcd_barrier(const XcdBarrier& b) {
;     ...
;             const unsigned og = xb_add(&bar[XB_TOP], 1u);
;             const unsigned tg = og / nx;
;             if (og + 1u == (tg + 1u) * nx) xb_add(&bar[XB_TOPGEN], 1u);
;             else XB_SPIN(xb_ld(&bar[XB_TOPGEN]) == tg, bar);
;             __builtin_amdgcn_fence(__ATOMIC_ACQUIRE, "agent");
;             xb_add(&bar[XB_XGEN(b.x)], 1u);
;             asm volatile("s_waitcnt vmcnt(0)" ::: "memory");
.LBB0_597:
	s_or_b64 exec, exec, s[6:7]
	s_mov_b64 s[6:7], exec
	v_mbcnt_lo_u32_b32 v0, s6, 0
	v_mbcnt_hi_u32_b32 v0, s7, v0
	v_cmp_eq_u32_e32 vcc, 0, v0
	s_waitcnt vmcnt(0)
	s_and_saveexec_b64 s[10:11], vcc
	s_cbranch_execz .LBB0_599
	s_bcnt1_i32_b64 s0, s[6:7]
	v_mov_b32_e32 v0, s0
	v_mov_b32_e32 v2, 0x2000
	s_nop 0

; __device__ __forceinline__ unsigned xb_ld(unsigned* p)              { return __hip_atomic_load(p, __ATOMIC_RELAXED, __HIP_MEMORY_SCOPE_AGENT); }
; __device__ __forceinline__ unsigned xb_add(unsigned* p, unsigned v) { return __hip_atomic_fetch_add(p, v, __ATOMIC_RELAXED, __HIP_MEMORY_SCOPE_AGENT); }
; #define XB_SPIN(cond, bar) do { unsigned _sp = 0; while (cond) { __builtin_amdgcn_s_sleep(1); \
;     if ((++_sp & 255u) == 0u) { if (xb_ld(&(bar)[XB_TMO])) break; if (_sp > XB_SPIN_CAP) { atomicAdd(&(bar)[XB_TMO], 1u); break; } } } } while (0)
; __device__ __forceinline__ void xcd_barrier(const XcdBarrier& b) {
;     ...
;             const unsigned og = xb_add(&bar[XB_TOP], 1u);
;             const unsigned tg = og / nx;
;             if (og + 1u == (tg + 1u) * nx) xb_add(&bar[XB_TOPGEN], 1u);
;             else XB_SPIN(xb_ld(&bar[XB_TOPGEN]) == tg, bar);
;             __builtin_amdgcn_fence(__ATOMIC_ACQUIRE, "agent");
;             xb_add(&bar[XB_XGEN(b.x)], 1u);
;             asm volatile("s_waitcnt vmcnt(0)" ::: "memory");
.LBB0_1244:
	s_or_b64 exec, exec, s[6:7]
	s_mov_b64 s[6:7], exec
	v_mbcnt_lo_u32_b32 v0, s6, 0
	v_mbcnt_hi_u32_b32 v0, s7, v0
	v_cmp_eq_u32_e32 vcc, 0, v0
	s_waitcnt vmcnt(0)
	s_and_saveexec_b64 s[10:11], vcc
	s_cbranch_execz .LBB0_270
	s_bcnt1_i32_b64 s0, s[6:7]
	v_mov_b32_e32 v0, s0
	v_mov_b32_e32 v2, 0x2000
	s_nop 0
	s_branch .LBB0_270
